# gl3 (GLA output items) middle section hand-scheduled: batched LDS reads for the 64 att@V/q@S MFMAs, branch-free causal mask, second-direction key loads issued with the first, gla_norm_g loaded once
# baseline (speedup 1.0000x reference)
; __device__ __forceinline__ unsigned f2bf(float f) { unsigned r; asm("v_cvt_pk_bf16_f32 %0, %1, %1" : "=v"(r) : "v"(f)); return r & 0xffffu; }
; __device__ __forceinline__ float silu_f(float x) { return x * sigmoid_f(x); }
; __device__ __forceinline__ float shx(float v, int m, int lane) { return __builtin_bit_cast(float, __builtin_amdgcn_ds_bpermute((lane ^ m) << 2, __builtin_bit_cast(int, v))); }
; __device__ __forceinline__ void gl3_item(PREF p, int l, int item, bool valid, LAS unsigned char* sl, int w4, int t256, int lane) {
;     ...
;         const float* gn = p.gla_norm_g + l * 512 + h * 128;
;         unsigned ogr[4][8];
; #pragma unroll
;         for (int j = 0; j < 4; ++j) { const size_t rowi = (size_t)(row0 + (16 * w4 + (lane >> 4) * 4 + j) * rstride);
; #pragma unroll
;             for (int nt = 0; nt < 8; ++nt) ogr[j][nt] = P[rowi * PW + 2048 + h * 128 + nt * 16 + (lane & 15)]; }
;         __builtin_amdgcn_sched_barrier(0);
; #pragma unroll
;         for (int j = 0; j < 4; ++j) {
;             float ss = 0.f;
; #pragma unroll
;             for (int nt = 0; nt < 8; ++nt) ss += o[nt][j] * o[nt][j];
;             ss += shx(ss, 1, lane); ss += shx(ss, 2, lane); ss += shx(ss, 4, lane); ss += shx(ss, 8, lane);
;             const float rs = __builtin_amdgcn_rsqf(ss * (1.f / 128.f) + 1e-6f);
;             const size_t rowi = (size_t)(row0 + (16 * w4 + (lane >> 4) * 4 + j) * rstride);
;             float ogv[8];
; #pragma unroll
;             for (int nt = 0; nt < 8; ++nt) ogv[nt] = bf2f(ogr[j][nt]);
; #pragma unroll
;             for (int nt = 0; nt < 8; ++nt) { const int vv = nt * 16 + (lane & 15);
;                 MIX[rowi * DM + 512 + h * 128 + vv] = (bf16_t)f2bf(o[nt][j] * rs * gn[vv] * silu_f(ogv[nt])); }
.Lgl3b_epi:
	v_lshl_add_u64 v[160:161], v[84:85], 2, s[88:89]
	v_lshlrev_b32_e32 v170, 2, v86
	v_lshlrev_b32_e32 v171, 2, v88
	global_load_dword v162, v[160:161], off
	global_load_dword v163, v[160:161], off offset:64
	global_load_dword v164, v[160:161], off offset:128
	global_load_dword v165, v170, s[88:89]
	global_load_dword v166, v[160:161], off offset:256
	global_load_dword v167, v[160:161], off offset:320
	global_load_dword v168, v[160:161], off offset:384
	global_load_dword v169, v171, s[88:89]
	v_mov_b32_e32 v32, s18
	v_readlane_b32 s18, v253, 53
	v_readlane_b32 s19, v253, 54
	v_mad_u32_u24 v36, s17, v92, v32
	v_add_u32_e32 v40, s17, v36
	v_mov_b64_e32 v[42:43], s[18:19]
	v_mad_i64_i32 v[32:33], s[18:19], v36, s46, v[42:43]
	v_lshl_add_u64 v[34:35], v[32:33], 0, s[90:91]
	v_lshlrev_b64 v[32:33], 1, v[84:85]
	v_lshl_add_u64 v[34:35], v[34:35], 0, v[32:33]
	v_lshl_add_u64 v[38:39], v[34:35], 0, s[70:71]
	v_add_co_u32_e32 v34, vcc, s33, v34
	v_ashrrev_i32_e32 v37, 31, v36
	s_nop 0
	v_addc_co_u32_e32 v35, vcc, 0, v35, vcc
	global_load_ushort v54, v[34:35], off
	global_load_ushort v55, v[38:39], off offset:32
	global_load_ushort v72, v[38:39], off offset:64
	global_load_ushort v73, v[38:39], off offset:96
	global_load_ushort v74, v[38:39], off offset:128
	global_load_ushort v75, v[38:39], off offset:160
	global_load_ushort v76, v[38:39], off offset:192
	global_load_ushort v77, v[38:39], off offset:224
	v_mad_i64_i32 v[34:35], s[18:19], v40, s46, v[42:43]
	v_lshl_add_u64 v[34:35], v[34:35], 0, s[90:91]
	v_lshl_add_u64 v[34:35], v[34:35], 0, v[32:33]
	v_lshl_add_u64 v[38:39], v[34:35], 0, s[70:71]
	v_add_co_u32_e32 v34, vcc, s33, v34
	v_ashrrev_i32_e32 v41, 31, v40
	s_nop 0
	v_addc_co_u32_e32 v35, vcc, 0, v35, vcc
	global_load_ushort v64, v[34:35], off
	global_load_ushort v65, v[38:39], off offset:32
	global_load_ushort v66, v[38:39], off offset:64
	global_load_ushort v67, v[38:39], off offset:96
	global_load_ushort v68, v[38:39], off offset:128
	global_load_ushort v69, v[38:39], off offset:160
	global_load_ushort v70, v[38:39], off offset:192
	global_load_ushort v71, v[38:39], off offset:224
	v_add_u32_e32 v38, s17, v40
	v_mad_i64_i32 v[34:35], s[18:19], v38, s46, v[42:43]
	v_lshl_add_u64 v[34:35], v[34:35], 0, s[90:91]
	v_lshl_add_u64 v[34:35], v[34:35], 0, v[32:33]
	v_lshl_add_u64 v[44:45], v[34:35], 0, s[70:71]
	v_add_co_u32_e32 v34, vcc, s33, v34
	v_ashrrev_i32_e32 v39, 31, v38
	s_nop 0
	v_addc_co_u32_e32 v35, vcc, 0, v35, vcc
	global_load_ushort v56, v[34:35], off
	global_load_ushort v57, v[44:45], off offset:32
	global_load_ushort v58, v[44:45], off offset:64
	global_load_ushort v59, v[44:45], off offset:96
	global_load_ushort v60, v[44:45], off offset:128
	global_load_ushort v61, v[44:45], off offset:160
	global_load_ushort v62, v[44:45], off offset:192
	global_load_ushort v63, v[44:45], off offset:224
	v_add_u32_e32 v34, s17, v38
	v_mad_i64_i32 v[42:43], s[18:19], v34, s46, v[42:43]
	v_lshl_add_u64 v[42:43], v[42:43], 0, s[90:91]
	v_lshl_add_u64 v[42:43], v[42:43], 0, v[32:33]
	v_lshl_add_u64 v[44:45], v[42:43], 0, s[70:71]
	v_add_co_u32_e32 v42, vcc, s33, v42
	v_ashrrev_i32_e32 v35, 31, v34
	s_nop 0
	v_addc_co_u32_e32 v43, vcc, 0, v43, vcc
	global_load_ushort v46, v[42:43], off
	global_load_ushort v47, v[44:45], off offset:32
	global_load_ushort v48, v[44:45], off offset:64
	global_load_ushort v49, v[44:45], off offset:96
	global_load_ushort v50, v[44:45], off offset:128
	global_load_ushort v51, v[44:45], off offset:160
	global_load_ushort v52, v[44:45], off offset:192
	global_load_ushort v53, v[44:45], off offset:224
	v_mul_f32_e32 v42, v28, v28
	v_fmac_f32_e32 v42, v24, v24
	v_fmac_f32_e32 v42, v20, v20
	v_fmac_f32_e32 v42, v16, v16
	v_fmac_f32_e32 v42, v12, v12
	v_fmac_f32_e32 v42, v8, v8
	v_fmac_f32_e32 v42, v4, v4
	v_fmac_f32_e32 v42, v0, v0
	ds_bpermute_b32 v43, v97, v42
	s_add_u32 vcc_lo, s12, s90
	s_addc_u32 vcc_hi, s13, 0
	v_lshlrev_b64 v[36:37], 11, v[36:37]
	s_waitcnt vmcnt(29)
	v_lshlrev_b32_e32 v78, 16, v72
	s_waitcnt lgkmcnt(0)
	v_add_f32_e32 v42, v42, v43
	ds_bpermute_b32 v43, v98, v42
	s_waitcnt vmcnt(24)
	v_lshlrev_b32_e32 v72, 16, v77
	v_lshlrev_b32_e32 v44, 16, v54
	v_mul_f32_e32 v45, 0xbfb8aa3b, v44
	v_exp_f32_e32 v45, v45
	s_waitcnt lgkmcnt(0)
	v_add_f32_e32 v42, v42, v43
	ds_bpermute_b32 v43, v99, v42
	v_lshlrev_b32_e32 v55, 16, v55
	v_add_f32_e32 v45, 1.0, v45
	v_rcp_f32_e32 v45, v45
	v_lshlrev_b32_e32 v79, 16, v74
	s_waitcnt lgkmcnt(0)
	v_add_f32_e32 v42, v42, v43
	ds_bpermute_b32 v43, v100, v42
	v_mul_f32_e32 v44, v45, v44
	v_mul_f32_e32 v74, 0xbfb8aa3b, v55
	v_exp_f32_e32 v74, v74
	v_lshlrev_b32_e32 v73, 16, v73
	s_waitcnt lgkmcnt(0)
	v_add_f32_e32 v42, v42, v43
	v_fmamk_f32 v42, v42, 0x3c000000, v220
	v_rsq_f32_e32 v77, v42
	v_lshl_add_u64 v[42:43], vcc, 0, v[36:37]
	v_lshl_add_u64 v[36:37], v[84:85], 2, s[88:89]
	v_mov_b32_e32 v54, v162
	v_mul_f32_e32 v24, v24, v77
	v_add_f32_e32 v74, 1.0, v74
	v_rcp_f32_e32 v74, v74
	v_lshlrev_b32_e32 v144, 1, v86
	v_lshlrev_b32_e32 v80, 16, v75
	v_mul_f32_e32 v8, v8, v77
	v_mul_f32_e32 v55, v74, v55
	v_lshl_add_u64 v[74:75], v[42:43], 0, v[144:145]
	v_lshlrev_b32_e32 v76, 16, v76
	v_mul_f32_e32 v4, v4, v77
	v_mul_f32_e32 v0, v0, v77
	v_lshlrev_b64 v[40:41], 11, v[40:41]
	v_lshl_add_u64 v[40:41], vcc, 0, v[40:41]
	s_waitcnt vmcnt(0)
; __device__ __forceinline__ unsigned f2bf(float f) { unsigned r; asm("v_cvt_pk_bf16_f32 %0, %1, %1" : "=v"(r) : "v"(f)); return r & 0xffffu; }
; __device__ __forceinline__ float silu_f(float x) { return x * sigmoid_f(x); }
; __device__ __forceinline__ float shx(float v, int m, int lane) { return __builtin_bit_cast(float, __builtin_amdgcn_ds_bpermute((lane ^ m) << 2, __builtin_bit_cast(int, v))); }
; __device__ __forceinline__ void gl3_item(PREF p, int l, int item, bool valid, LAS unsigned char* sl, int w4, int t256, int lane) {
;     ...
;         for (int j = 0; j < 4; ++j) {
;             float ss = 0.f;
; #pragma unroll
;             for (int nt = 0; nt < 8; ++nt) ss += o[nt][j] * o[nt][j];
;             ss += shx(ss, 1, lane); ss += shx(ss, 2, lane); ss += shx(ss, 4, lane); ss += shx(ss, 8, lane);
;             const float rs = __builtin_amdgcn_rsqf(ss * (1.f / 128.f) + 1e-6f);
;             const size_t rowi = (size_t)(row0 + (16 * w4 + (lane >> 4) * 4 + j) * rstride);
;             float ogv[8];
; #pragma unroll
;             for (int nt = 0; nt < 8; ++nt) ogv[nt] = bf2f(ogr[j][nt]);
; #pragma unroll
;             for (int nt = 0; nt < 8; ++nt) { const int vv = nt * 16 + (lane & 15);
;                 MIX[rowi * DM + 512 + h * 128 + vv] = (bf16_t)f2bf(o[nt][j] * rs * gn[vv] * silu_f(ogv[nt])); }
	v_mul_f32_e32 v24, v54, v24
	v_mul_f32_e32 v24, v44, v24
	v_cvt_pk_bf16_f32 v24, v24, v24
	v_lshl_add_u64 v[44:45], v[42:43], 0, v[32:33]
	global_store_short v[44:45], v24, off
	v_mul_f32_e32 v24, v28, v77
	v_mov_b32_e32 v28, v163
	v_mul_f32_e32 v24, v28, v24
	v_mul_f32_e32 v24, v55, v24
	v_cvt_pk_bf16_f32 v24, v24, v24
	global_store_short v[44:45], v24, off offset:32
	v_mul_f32_e32 v24, v20, v77
	v_mov_b32_e32 v20, v164
	v_mul_f32_e32 v55, 0xbfb8aa3b, v78
	v_exp_f32_e32 v55, v55
	v_mul_f32_e32 v24, v24, v20
	v_add_f32_e32 v55, 1.0, v55
	v_rcp_f32_e32 v55, v55
	s_nop 0
	v_mul_f32_e32 v55, v55, v78
	v_mul_f32_e32 v24, v55, v24
	v_cvt_pk_bf16_f32 v24, v24, v24
	global_store_short v[44:45], v24, off offset:64
	v_mul_f32_e32 v24, v16, v77
	v_lshlrev_b32_e32 v16, 2, v86
	v_mov_b32_e32 v16, v165
	v_mul_f32_e32 v55, 0xbfb8aa3b, v73
	v_exp_f32_e32 v55, v55
	v_mul_f32_e32 v24, v24, v16
	v_add_f32_e32 v55, 1.0, v55
	v_rcp_f32_e32 v55, v55
	s_nop 0
	v_mul_f32_e32 v55, v55, v73
	v_mul_f32_e32 v24, v55, v24
	v_cvt_pk_bf16_f32 v24, v24, v24
	global_store_short v[74:75], v24, off
	v_mul_f32_e32 v24, v12, v77
	v_mov_b32_e32 v12, v166
	v_mul_f32_e32 v55, 0xbfb8aa3b, v79
	v_exp_f32_e32 v55, v55
	v_mul_f32_e32 v24, v24, v12
	v_add_f32_e32 v55, 1.0, v55
	v_rcp_f32_e32 v55, v55
	s_nop 0
	v_mul_f32_e32 v55, v55, v79
	v_mul_f32_e32 v24, v55, v24
	v_mov_b32_e32 v55, v167
	v_cvt_pk_bf16_f32 v24, v24, v24
	global_store_short v[44:45], v24, off offset:128
	v_mul_f32_e32 v24, 0xbfb8aa3b, v80
	v_exp_f32_e32 v24, v24
	v_mul_f32_e32 v8, v8, v55
	v_add_f32_e32 v24, 1.0, v24
	v_rcp_f32_e32 v24, v24
	s_nop 0
	v_mul_f32_e32 v24, v24, v80
	v_mul_f32_e32 v8, v24, v8
	v_cvt_pk_bf16_f32 v8, v8, v8
	global_store_short v[44:45], v8, off offset:160
	v_mov_b32_e32 v8, v168
	v_mul_f32_e32 v24, 0xbfb8aa3b, v76
	v_exp_f32_e32 v24, v24
	v_lshlrev_b32_e32 v36, 1, v88
	v_mov_b32_e32 v37, v145
	v_lshl_add_u64 v[42:43], v[42:43], 0, v[36:37]
	v_add_f32_e32 v24, 1.0, v24
	v_rcp_f32_e32 v24, v24
	v_mul_f32_e32 v4, v4, v8
	v_mul_f32_e32 v24, v24, v76
	v_mul_f32_e32 v4, v24, v4
	v_cvt_pk_bf16_f32 v4, v4, v4
	global_store_short v[44:45], v4, off offset:192
	v_lshlrev_b32_e32 v4, 2, v88
	v_mov_b32_e32 v44, v169
	v_mul_f32_e32 v4, 0xbfb8aa3b, v72
	v_exp_f32_e32 v4, v4
	v_lshlrev_b32_e32 v45, 16, v67
	v_lshlrev_b32_e32 v67, 16, v71
	v_add_f32_e32 v4, 1.0, v4
	v_rcp_f32_e32 v4, v4
	v_mul_f32_e32 v0, v0, v44
	v_mul_f32_e32 v4, v4, v72
	v_mul_f32_e32 v0, v4, v0
	v_cvt_pk_bf16_f32 v0, v0, v0
	global_store_short v[42:43], v0, off
	v_mul_f32_e32 v0, v29, v29
	v_fmac_f32_e32 v0, v25, v25
	v_fmac_f32_e32 v0, v21, v21
	v_fmac_f32_e32 v0, v17, v17
	v_fmac_f32_e32 v0, v13, v13
	v_fmac_f32_e32 v0, v9, v9
	v_fmac_f32_e32 v0, v5, v5
	v_fmac_f32_e32 v0, v1, v1
	ds_bpermute_b32 v4, v97, v0
	v_lshlrev_b32_e32 v42, 16, v65
	v_lshlrev_b32_e32 v43, 16, v66
	v_lshlrev_b32_e32 v65, 16, v69
	v_lshlrev_b32_e32 v66, 16, v70
	s_waitcnt lgkmcnt(0)
	v_add_f32_e32 v0, v0, v4
	ds_bpermute_b32 v4, v98, v0
	s_waitcnt lgkmcnt(0)
	v_add_f32_e32 v0, v0, v4
	ds_bpermute_b32 v4, v99, v0
	s_waitcnt lgkmcnt(0)
	v_add_f32_e32 v0, v0, v4
	ds_bpermute_b32 v4, v100, v0
	s_waitcnt lgkmcnt(0)
	v_add_f32_e32 v0, v0, v4
	v_fmamk_f32 v0, v0, 0x3c000000, v220
	v_rsq_f32_e32 v0, v0
	v_lshlrev_b32_e32 v4, 16, v64
	v_lshlrev_b32_e32 v64, 16, v68
	v_mul_f32_e32 v24, v25, v0
	v_mul_f32_e32 v25, 0xbfb8aa3b, v4
	v_exp_f32_e32 v25, v25
	v_mul_f32_e32 v24, v54, v24
	v_add_f32_e32 v25, 1.0, v25
	v_rcp_f32_e32 v25, v25
	s_nop 0
	v_mul_f32_e32 v4, v25, v4
	v_mul_f32_e32 v4, v4, v24
	v_cvt_pk_bf16_f32 v4, v4, v4
	v_lshl_add_u64 v[24:25], v[40:41], 0, v[32:33]
	global_store_short v[24:25], v4, off
	v_mul_f32_e32 v4, v29, v0
	v_mul_f32_e32 v29, 0xbfb8aa3b, v42
	v_exp_f32_e32 v29, v29
	v_mul_f32_e32 v4, v28, v4
	v_add_f32_e32 v29, 1.0, v29
	v_rcp_f32_e32 v29, v29
	s_nop 0
	v_mul_f32_e32 v29, v29, v42
	v_mul_f32_e32 v4, v29, v4
	v_cvt_pk_bf16_f32 v4, v4, v4
	global_store_short v[24:25], v4, off offset:32
	v_mul_f32_e32 v4, v21, v0
	v_mul_f32_e32 v21, 0xbfb8aa3b, v43
	v_exp_f32_e32 v21, v21
	v_mul_f32_e32 v4, v20, v4
	v_lshlrev_b32_e32 v29, 16, v61
	v_add_f32_e32 v21, 1.0, v21
	v_rcp_f32_e32 v21, v21
	s_nop 0
	v_mul_f32_e32 v21, v21, v43
	v_mul_f32_e32 v4, v21, v4
	v_cvt_pk_bf16_f32 v4, v4, v4
	global_store_short v[24:25], v4, off offset:64
	v_mul_f32_e32 v4, v17, v0
	v_mul_f32_e32 v17, 0xbfb8aa3b, v45
	v_exp_f32_e32 v17, v17
	v_mul_f32_e32 v4, v16, v4
	v_lshl_add_u64 v[42:43], v[40:41], 0, v[144:145]
	v_lshlrev_b32_e32 v21, 16, v60
	v_add_f32_e32 v17, 1.0, v17
	v_rcp_f32_e32 v17, v17
	s_nop 0
	v_mul_f32_e32 v17, v17, v45
	v_mul_f32_e32 v4, v17, v4
	v_cvt_pk_bf16_f32 v4, v4, v4
	global_store_short v[42:43], v4, off
	v_mul_f32_e32 v4, v13, v0
	v_mul_f32_e32 v13, 0xbfb8aa3b, v64
	v_exp_f32_e32 v13, v13
	v_mul_f32_e32 v4, v12, v4
	v_lshlrev_b32_e32 v17, 16, v59
	v_add_f32_e32 v13, 1.0, v13
	v_rcp_f32_e32 v13, v13
	s_nop 0
	v_mul_f32_e32 v13, v13, v64
	v_mul_f32_e32 v4, v13, v4
	v_cvt_pk_bf16_f32 v4, v4, v4
	global_store_short v[24:25], v4, off offset:128
	v_mul_f32_e32 v4, v9, v0
	v_mul_f32_e32 v9, 0xbfb8aa3b, v65
	v_exp_f32_e32 v9, v9
	v_mul_f32_e32 v4, v55, v4
	v_lshlrev_b32_e32 v13, 16, v58
	v_add_f32_e32 v9, 1.0, v9
	v_rcp_f32_e32 v9, v9
	s_nop 0
	v_mul_f32_e32 v9, v9, v65
	v_mul_f32_e32 v4, v9, v4
	v_cvt_pk_bf16_f32 v4, v4, v4
	global_store_short v[24:25], v4, off offset:160
	v_mul_f32_e32 v4, v5, v0
	v_mul_f32_e32 v5, 0xbfb8aa3b, v66
	v_exp_f32_e32 v5, v5
	v_mul_f32_e32 v0, v1, v0
	v_mul_f32_e32 v1, 0xbfb8aa3b, v67
	v_exp_f32_e32 v1, v1
	v_add_f32_e32 v5, 1.0, v5
	v_rcp_f32_e32 v5, v5
	v_mul_f32_e32 v4, v8, v4
	v_add_f32_e32 v1, 1.0, v1
	v_rcp_f32_e32 v1, v1
	v_mul_f32_e32 v5, v5, v66
	v_mul_f32_e32 v4, v5, v4
	v_mul_f32_e32 v0, v44, v0
	v_mul_f32_e32 v1, v1, v67
	v_cvt_pk_bf16_f32 v4, v4, v4
	v_mul_f32_e32 v0, v1, v0
	global_store_short v[24:25], v4, off offset:192
	v_cvt_pk_bf16_f32 v4, v0, v0
	v_lshl_add_u64 v[0:1], v[40:41], 0, v[36:37]
	global_store_short v[0:1], v4, off
	v_mul_f32_e32 v0, v30, v30
	v_fmac_f32_e32 v0, v26, v26
	v_fmac_f32_e32 v0, v22, v22
	v_fmac_f32_e32 v0, v18, v18
	v_fmac_f32_e32 v0, v14, v14
	v_fmac_f32_e32 v0, v10, v10
	v_fmac_f32_e32 v0, v6, v6
	v_fmac_f32_e32 v0, v2, v2
	ds_bpermute_b32 v1, v97, v0
	v_lshlrev_b32_e32 v4, 16, v56
	v_mul_f32_e32 v24, 0xbfb8aa3b, v4
	v_exp_f32_e32 v24, v24
	v_lshlrev_b32_e32 v9, 16, v57
	s_waitcnt lgkmcnt(0)
; __device__ __forceinline__ unsigned f2bf(float f) { unsigned r; asm("v_cvt_pk_bf16_f32 %0, %1, %1" : "=v"(r) : "v"(f)); return r & 0xffffu; }
; __device__ __forceinline__ float silu_f(float x) { return x * sigmoid_f(x); }
; __device__ __forceinline__ float shx(float v, int m, int lane) { return __builtin_bit_cast(float, __builtin_amdgcn_ds_bpermute((lane ^ m) << 2, __builtin_bit_cast(int, v))); }
; __device__ __forceinline__ void gl3_item(PREF p, int l, int item, bool valid, LAS unsigned char* sl, int w4, int t256, int lane) {
;     ...
;         for (int j = 0; j < 4; ++j) {
;             float ss = 0.f;
; #pragma unroll
;             for (int nt = 0; nt < 8; ++nt) ss += o[nt][j] * o[nt][j];
;             ss += shx(ss, 1, lane); ss += shx(ss, 2, lane); ss += shx(ss, 4, lane); ss += shx(ss, 8, lane);
;             const float rs = __builtin_amdgcn_rsqf(ss * (1.f / 128.f) + 1e-6f);
;             const size_t rowi = (size_t)(row0 + (16 * w4 + (lane >> 4) * 4 + j) * rstride);
;             float ogv[8];
; #pragma unroll
;             for (int nt = 0; nt < 8; ++nt) ogv[nt] = bf2f(ogr[j][nt]);
; #pragma unroll
;             for (int nt = 0; nt < 8; ++nt) { const int vv = nt * 16 + (lane & 15);
;                 MIX[rowi * DM + 512 + h * 128 + vv] = (bf16_t)f2bf(o[nt][j] * rs * gn[vv] * silu_f(ogv[nt])); }
	v_add_f32_e32 v0, v0, v1
	ds_bpermute_b32 v1, v98, v0
	v_mul_f32_e32 v25, 0xbfb8aa3b, v9
	v_add_f32_e32 v24, 1.0, v24
	v_exp_f32_e32 v25, v25
	v_rcp_f32_e32 v24, v24
	s_waitcnt lgkmcnt(0)
	v_add_f32_e32 v0, v0, v1
	ds_bpermute_b32 v1, v99, v0
	v_add_f32_e32 v25, 1.0, v25
	v_mul_f32_e32 v4, v24, v4
	v_rcp_f32_e32 v25, v25
	v_lshlrev_b32_e32 v40, 16, v62
	s_waitcnt lgkmcnt(0)
	v_add_f32_e32 v0, v0, v1
	ds_bpermute_b32 v1, v100, v0
	v_mul_f32_e32 v9, v25, v9
	v_lshlrev_b32_e32 v41, 16, v63
	s_waitcnt lgkmcnt(0)
	v_add_f32_e32 v0, v0, v1
	v_fmamk_f32 v0, v0, 0x3c000000, v220
	v_rsq_f32_e32 v42, v0
	v_lshlrev_b64 v[0:1], 11, v[38:39]
	v_lshl_add_u64 v[0:1], vcc, 0, v[0:1]
	v_mul_f32_e32 v5, v26, v42
	v_mul_f32_e32 v5, v54, v5
	v_mul_f32_e32 v4, v4, v5
	v_cvt_pk_bf16_f32 v24, v4, v4
	v_lshl_add_u64 v[4:5], v[0:1], 0, v[32:33]
	global_store_short v[4:5], v24, off
	v_mul_f32_e32 v24, v30, v42
	v_mul_f32_e32 v24, v28, v24
	v_mul_f32_e32 v9, v9, v24
	v_cvt_pk_bf16_f32 v9, v9, v9
	global_store_short v[4:5], v9, off offset:32
	v_mul_f32_e32 v9, v22, v42
	v_mul_f32_e32 v22, 0xbfb8aa3b, v13
	v_exp_f32_e32 v22, v22
	v_mul_f32_e32 v9, v20, v9
	v_lshl_add_u64 v[24:25], v[0:1], 0, v[144:145]
	v_mul_f32_e32 v6, v6, v42
	v_add_f32_e32 v22, 1.0, v22
	v_rcp_f32_e32 v22, v22
	v_mul_f32_e32 v6, v8, v6
	v_mul_f32_e32 v2, v2, v42
	v_mul_f32_e32 v2, v44, v2
	v_mul_f32_e32 v13, v22, v13
	v_mul_f32_e32 v9, v13, v9
	v_mul_f32_e32 v13, 0xbfb8aa3b, v17
	v_exp_f32_e32 v13, v13
	v_cvt_pk_bf16_f32 v9, v9, v9
	global_store_short v[4:5], v9, off offset:64
	v_mul_f32_e32 v9, v18, v42
	v_add_f32_e32 v13, 1.0, v13
	v_rcp_f32_e32 v13, v13
	v_mul_f32_e32 v9, v16, v9
	v_lshl_add_u64 v[0:1], v[0:1], 0, v[36:37]
	v_lshlrev_b32_e32 v18, 16, v52
	v_mul_f32_e32 v13, v13, v17
	v_mul_f32_e32 v9, v13, v9
	v_mul_f32_e32 v13, 0xbfb8aa3b, v21
	v_exp_f32_e32 v13, v13
	v_cvt_pk_bf16_f32 v9, v9, v9
	global_store_short v[24:25], v9, off
	v_mul_f32_e32 v9, v14, v42
	v_add_f32_e32 v13, 1.0, v13
	v_rcp_f32_e32 v13, v13
	v_mul_f32_e32 v9, v12, v9
	v_lshlrev_b32_e32 v14, 16, v51
	v_mul_f32_e32 v13, v13, v21
	v_mul_f32_e32 v9, v13, v9
	v_cvt_pk_bf16_f32 v9, v9, v9
	global_store_short v[4:5], v9, off offset:128
	v_mul_f32_e32 v9, v10, v42
	v_mul_f32_e32 v10, 0xbfb8aa3b, v29
	v_exp_f32_e32 v10, v10
	v_mul_f32_e32 v9, v55, v9
	v_lshlrev_b32_e32 v13, 16, v50
	v_lshlrev_b32_e32 v21, 16, v53
	v_add_f32_e32 v10, 1.0, v10
	v_rcp_f32_e32 v10, v10
	s_nop 0
	v_mul_f32_e32 v10, v10, v29
	v_mul_f32_e32 v9, v10, v9
	v_cvt_pk_bf16_f32 v9, v9, v9
	global_store_short v[4:5], v9, off offset:160
	v_mul_f32_e32 v9, 0xbfb8aa3b, v40
	v_exp_f32_e32 v9, v9
	v_lshlrev_b32_e32 v10, 16, v49
	v_add_f32_e32 v9, 1.0, v9
	v_rcp_f32_e32 v9, v9
	s_nop 0
	v_mul_f32_e32 v9, v9, v40
	v_mul_f32_e32 v6, v9, v6
	v_cvt_pk_bf16_f32 v6, v6, v6
	global_store_short v[4:5], v6, off offset:192
	v_mul_f32_e32 v4, 0xbfb8aa3b, v41
	v_exp_f32_e32 v4, v4
	v_lshlrev_b32_e32 v6, 16, v47
	v_mul_f32_e32 v17, 0xbfb8aa3b, v6
	v_exp_f32_e32 v17, v17
	v_add_f32_e32 v4, 1.0, v4
	v_rcp_f32_e32 v4, v4
	v_lshlrev_b32_e32 v9, 16, v48
	v_add_f32_e32 v17, 1.0, v17
	v_rcp_f32_e32 v17, v17
	v_mul_f32_e32 v4, v4, v41
	v_mul_f32_e32 v2, v4, v2
	v_cvt_pk_bf16_f32 v2, v2, v2
	global_store_short v[0:1], v2, off
	v_mul_f32_e32 v0, v31, v31
	v_fmac_f32_e32 v0, v27, v27
	v_fmac_f32_e32 v0, v23, v23
	v_fmac_f32_e32 v0, v19, v19
	v_fmac_f32_e32 v0, v15, v15
	v_fmac_f32_e32 v0, v11, v11
	v_fmac_f32_e32 v0, v7, v7
	v_fmac_f32_e32 v0, v3, v3
	ds_bpermute_b32 v1, v97, v0
	v_lshlrev_b32_e32 v2, 16, v46
	v_mul_f32_e32 v5, 0xbfb8aa3b, v2
	v_exp_f32_e32 v5, v5
	v_mul_f32_e32 v6, v17, v6
	s_waitcnt lgkmcnt(0)
	v_add_f32_e32 v0, v0, v1
	ds_bpermute_b32 v1, v98, v0
	v_add_f32_e32 v5, 1.0, v5
	v_rcp_f32_e32 v5, v5
	s_waitcnt lgkmcnt(0)
	v_add_f32_e32 v0, v0, v1
	ds_bpermute_b32 v1, v99, v0
	v_mul_f32_e32 v2, v5, v2
	s_waitcnt lgkmcnt(0)
	v_add_f32_e32 v0, v0, v1
	ds_bpermute_b32 v1, v100, v0
	s_waitcnt lgkmcnt(0)
	v_add_f32_e32 v0, v0, v1
	v_fmamk_f32 v0, v0, 0x3c000000, v220
	v_rsq_f32_e32 v22, v0
	v_lshlrev_b64 v[0:1], 11, v[34:35]
	v_lshl_add_u64 v[0:1], vcc, 0, v[0:1]
	v_mul_f32_e32 v4, v27, v22
	v_mul_f32_e32 v4, v54, v4
	v_mul_f32_e32 v2, v2, v4
	v_cvt_pk_bf16_f32 v2, v2, v2
	v_lshl_add_u64 v[4:5], v[0:1], 0, v[32:33]
	global_store_short v[4:5], v2, off
	v_mul_f32_e32 v2, v31, v22
	v_mul_f32_e32 v2, v28, v2
	v_mul_f32_e32 v2, v6, v2
	v_mul_f32_e32 v6, 0xbfb8aa3b, v9
	v_exp_f32_e32 v6, v6
	v_cvt_pk_bf16_f32 v2, v2, v2
	global_store_short v[4:5], v2, off offset:32
	v_mul_f32_e32 v2, v23, v22
	v_add_f32_e32 v6, 1.0, v6
	v_rcp_f32_e32 v6, v6
	v_mul_f32_e32 v2, v20, v2
	v_mul_f32_e32 v6, v6, v9
	v_mul_f32_e32 v2, v6, v2
	v_mul_f32_e32 v6, 0xbfb8aa3b, v10
	v_exp_f32_e32 v6, v6
	v_cvt_pk_bf16_f32 v2, v2, v2
	global_store_short v[4:5], v2, off offset:64
	v_mul_f32_e32 v2, v19, v22
	v_add_f32_e32 v6, 1.0, v6
	v_rcp_f32_e32 v6, v6
	v_mul_f32_e32 v2, v16, v2
	v_lshl_add_u64 v[16:17], v[0:1], 0, v[144:145]
	v_lshl_add_u64 v[0:1], v[0:1], 0, v[36:37]
	v_mul_f32_e32 v6, v6, v10
	v_mul_f32_e32 v2, v6, v2
	v_mul_f32_e32 v6, 0xbfb8aa3b, v13
	v_exp_f32_e32 v6, v6
	v_cvt_pk_bf16_f32 v2, v2, v2
	global_store_short v[16:17], v2, off
	v_mul_f32_e32 v2, v15, v22
	v_add_f32_e32 v6, 1.0, v6
	v_rcp_f32_e32 v6, v6
	v_mul_f32_e32 v2, v12, v2
	v_mul_f32_e32 v6, v6, v13
	v_mul_f32_e32 v2, v6, v2
	v_mul_f32_e32 v6, 0xbfb8aa3b, v14
	v_exp_f32_e32 v6, v6
	v_cvt_pk_bf16_f32 v2, v2, v2
	global_store_short v[4:5], v2, off offset:128
	v_mul_f32_e32 v2, v11, v22
	v_add_f32_e32 v6, 1.0, v6
	v_rcp_f32_e32 v6, v6
	v_mul_f32_e32 v2, v55, v2
	v_mul_f32_e32 v6, v6, v14
	v_mul_f32_e32 v2, v6, v2
	v_mul_f32_e32 v6, 0xbfb8aa3b, v18
	v_exp_f32_e32 v6, v6
	v_cvt_pk_bf16_f32 v2, v2, v2
	global_store_short v[4:5], v2, off offset:160
	v_mul_f32_e32 v2, v7, v22
	v_add_f32_e32 v6, 1.0, v6
	v_rcp_f32_e32 v6, v6
	v_mul_f32_e32 v2, v8, v2
	v_mul_f32_e32 v6, v6, v18
	v_mul_f32_e32 v2, v6, v2
	v_cvt_pk_bf16_f32 v2, v2, v2
	global_store_short v[4:5], v2, off offset:192
	v_mul_f32_e32 v2, v3, v22
	v_mul_f32_e32 v3, 0xbfb8aa3b, v21
	v_exp_f32_e32 v3, v3
	v_mul_f32_e32 v2, v44, v2
	v_add_f32_e32 v3, 1.0, v3
	v_rcp_f32_e32 v3, v3
	s_nop 0
	v_mul_f32_e32 v3, v3, v21
	v_mul_f32_e32 v2, v3, v2
	v_cvt_pk_bf16_f32 v2, v2, v2
	global_store_short v[0:1], v2, off

; __device__ __forceinline__ void gl3_item(PREF p, int l, int item, bool valid, LAS unsigned char* sl, int w4, int t256, int lane) {
;     ...
;     if (valid) {
;         unsigned vr[16]; u32x4 sv[2][4];
; #pragma unroll
;         for (int ii = 0; ii < 16; ++ii) { const int i = 16 * w4 + ii; vr[ii] = *(const unsigned*)(P + (size_t)(row0 + i * rstride) * PW + 1536 + h * 128 + 2 * lane); }
; #pragma unroll
;         for (int d = 0; d < 2; ++d) { const bf16_t* Sg = (const bf16_t*)GLS + (size_t)(((b * 4 + h) * 2 + d) * NCH + cj) * 8192;
; #pragma unroll
;             for (int r = 0; r < 4; ++r) sv[d][r] = *(const u32x4*)(Sg + (r * 256 + t256) * 8); }
; #pragma unroll
;         for (int d = 0; d < 2; ++d)
; #pragma unroll
;             for (int ks = 0; ks < 2; ++ks) Aq[d][ks] = *(const bf16x8*)(QK + rowi_a * 1024 + d * 512 + h * 64 + ks * 32 + (lane >> 4) * 8);
; #pragma unroll
;         for (int nt = 0; nt < 4; ++nt) { const size_t rows = (size_t)(row0 + (nt * 16 + (lane & 15)) * rstride);
; #pragma unroll
;             for (int ks = 0; ks < 2; ++ks) Bk[nt][ks] = *(const bf16x8*)(QK + rows * 1024 + 256 + h * 64 + ks * 32 + (lane >> 4) * 8); }
.LBB0_90:
	s_cmp_lt_i32 s59, s47
	s_cselect_b64 s[88:89], -1, 0
	s_and_b32 s16, s59, 3
	s_cmp_ge_i32 s59, s47
	s_cbranch_scc1 .LBB0_92
	s_and_b64 s[70:71], s[86:87], exec
	s_cselect_b32 s19, s46, s19
	s_cselect_b32 s46, s58, s33
	s_mul_i32 s33, s17, s9
	s_add_i32 s70, s33, s18
	s_lshl_b32 s90, s16, 7
	s_mul_i32 s58, s70, 0x1600
	v_readlane_b32 s86, v253, 53
	s_mul_hi_i32 s33, s70, 0x1600
	v_readlane_b32 s87, v253, 54
	s_add_u32 s58, s86, s58
	s_addc_u32 s59, s87, s33
	s_lshl_b32 s33, s16, 8
	s_add_u32 s58, s58, s33
	s_addc_u32 s59, s59, 0
	s_add_i32 s70, s70, s17
	global_load_dword v112, v101, s[58:59] offset:3072
	s_mul_i32 s59, s70, 0x1600
	s_mul_hi_i32 s58, s70, 0x1600
	s_add_u32 s59, s86, s59
	s_addc_u32 s71, s87, s58
	s_add_u32 s58, s59, s33
	s_addc_u32 s59, s71, 0
	s_add_i32 s70, s70, s17
	global_load_dword v113, v101, s[58:59] offset:3072
	s_mul_i32 s59, s70, 0x1600
	s_mul_hi_i32 s58, s70, 0x1600
	s_add_u32 s59, s86, s59
	s_addc_u32 s71, s87, s58
	s_add_u32 s58, s59, s33
	s_addc_u32 s59, s71, 0
	s_add_i32 s70, s70, s17
	global_load_dword v114, v101, s[58:59] offset:3072
	s_mul_i32 s59, s70, 0x1600
	s_mul_hi_i32 s58, s70, 0x1600
	s_add_u32 s59, s86, s59
	s_addc_u32 s71, s87, s58
	s_add_u32 s58, s59, s33
	s_addc_u32 s59, s71, 0
	s_add_i32 s70, s70, s17
	global_load_dword v115, v101, s[58:59] offset:3072
	s_mul_i32 s59, s70, 0x1600
	s_mul_hi_i32 s58, s70, 0x1600
	s_add_u32 s59, s86, s59
	s_addc_u32 s71, s87, s58
	s_add_u32 s58, s59, s33
	s_addc_u32 s59, s71, 0
	s_add_i32 s70, s70, s17
	global_load_dword v116, v101, s[58:59] offset:3072
	s_mul_i32 s59, s70, 0x1600
	s_mul_hi_i32 s58, s70, 0x1600
	s_add_u32 s59, s86, s59
	s_addc_u32 s71, s87, s58
	s_add_u32 s58, s59, s33
	s_addc_u32 s59, s71, 0
	s_add_i32 s70, s70, s17
	global_load_dword v117, v101, s[58:59] offset:3072
	s_mul_i32 s59, s70, 0x1600
	s_mul_hi_i32 s58, s70, 0x1600
	s_add_u32 s59, s86, s59
	s_addc_u32 s71, s87, s58
	s_add_u32 s58, s59, s33
	s_addc_u32 s59, s71, 0
	s_add_i32 s70, s70, s17
	global_load_dword v118, v101, s[58:59] offset:3072
	s_mul_i32 s59, s70, 0x1600
	s_mul_hi_i32 s58, s70, 0x1600
	s_add_u32 s59, s86, s59
	s_addc_u32 s71, s87, s58
	s_add_u32 s58, s59, s33
	s_addc_u32 s59, s71, 0
	s_add_i32 s70, s70, s17
	global_load_dword v119, v101, s[58:59] offset:3072
	s_mul_i32 s59, s70, 0x1600
	s_mul_hi_i32 s58, s70, 0x1600
	s_add_u32 s59, s86, s59
	s_addc_u32 s71, s87, s58
	s_add_u32 s58, s59, s33
	s_addc_u32 s59, s71, 0
	s_add_i32 s70, s70, s17
	global_load_dword v120, v101, s[58:59] offset:3072
	s_mul_i32 s59, s70, 0x1600
	s_mul_hi_i32 s58, s70, 0x1600
	s_add_u32 s59, s86, s59
	s_addc_u32 s71, s87, s58
	s_add_u32 s58, s59, s33
	s_addc_u32 s59, s71, 0
	s_add_i32 s70, s70, s17
	global_load_dword v121, v101, s[58:59] offset:3072
	s_mul_i32 s59, s70, 0x1600
	s_mul_hi_i32 s58, s70, 0x1600
	s_add_u32 s59, s86, s59
	s_addc_u32 s71, s87, s58
	s_add_u32 s58, s59, s33
	s_addc_u32 s59, s71, 0
	s_add_i32 s70, s70, s17
	global_load_dword v122, v101, s[58:59] offset:3072
	s_mul_i32 s59, s70, 0x1600
	s_mul_hi_i32 s58, s70, 0x1600
	s_add_u32 s59, s86, s59
	s_addc_u32 s71, s87, s58
	s_add_u32 s58, s59, s33
	s_addc_u32 s59, s71, 0
	s_add_i32 s70, s70, s17
	global_load_dword v123, v101, s[58:59] offset:3072
	s_mul_i32 s59, s70, 0x1600
	s_mul_hi_i32 s58, s70, 0x1600
	s_add_u32 s59, s86, s59
	s_addc_u32 s71, s87, s58
	s_add_u32 s58, s59, s33
	s_addc_u32 s59, s71, 0
	s_add_i32 s70, s70, s17
	global_load_dword v124, v101, s[58:59] offset:3072
	s_mul_i32 s59, s70, 0x1600
	s_mul_hi_i32 s58, s70, 0x1600
	s_add_u32 s59, s86, s59
	s_addc_u32 s71, s87, s58
	s_add_u32 s58, s59, s33
	s_addc_u32 s59, s71, 0
	s_add_i32 s70, s70, s17
	global_load_dword v125, v101, s[58:59] offset:3072
	s_mul_i32 s59, s70, 0x1600
	s_mul_hi_i32 s58, s70, 0x1600
	s_add_u32 s59, s86, s59
	s_addc_u32 s71, s87, s58
	s_add_u32 s58, s59, s33
	s_addc_u32 s59, s71, 0
	global_load_dword v126, v101, s[58:59] offset:3072
	s_add_i32 s58, s70, s17
	s_mul_hi_i32 s59, s58, 0x1600
	s_mulk_i32 s58, 0x1600
	s_add_u32 s58, s86, s58
	s_addc_u32 s59, s87, s59
	s_add_u32 s58, s58, s33
	s_addc_u32 s59, s59, 0
	s_lshl_b32 s33, s46, 3
	s_lshl_b32 s46, s16, 1
	s_or_b32 s33, s33, s46
	s_mulk_i32 s33, 0x104
	global_load_dword v127, v101, s[58:59] offset:3072
	s_add_i32 s58, s33, s19
	s_ashr_i32 s59, s58, 31
	s_lshl_b64 s[70:71], s[58:59], 14
	s_add_u32 s70, s7, s70
	s_addc_u32 s71, s8, s71
	s_addk_i32 s58, 0x104
	s_ashr_i32 s59, s58, 31
	s_lshl_b64 s[58:59], s[58:59], 14
	s_waitcnt vmcnt(17)
	v_mov_b32_e32 v40, s18
	s_add_u32 s58, s7, s58
	s_addc_u32 s59, s8, s59
	v_mad_u32_u24 v20, s17, v84, v40
	s_lshl_b32 s19, s17, 4
	v_mad_u32_u24 v0, s17, v87, v40
	v_add_u32_e32 v28, s19, v20
	v_ashrrev_i32_e32 v1, 31, v0
	v_ashrrev_i32_e32 v21, 31, v20
	v_ashrrev_i32_e32 v29, 31, v28
	v_lshlrev_b64 v[0:1], 11, v[0:1]
	v_lshlrev_b64 v[12:13], 11, v[20:21]
	v_lshlrev_b64 v[20:21], 11, v[28:29]
	v_add_u32_e32 v28, s19, v28
	v_mad_u32_u24 v40, s17, v86, v40
	v_lshl_add_u64 v[0:1], s[0:1], 0, v[0:1]
	v_ashrrev_i32_e32 v29, 31, v28
	v_ashrrev_i32_e32 v41, 31, v40
	v_lshl_add_u64 v[0:1], v[0:1], 0, s[90:91]
	v_lshlrev_b64 v[28:29], 11, v[28:29]
	v_lshlrev_b64 v[40:41], 11, v[40:41]
	v_lshl_add_u64 v[0:1], v[0:1], 0, v[90:91]
	v_lshl_add_u64 v[12:13], s[0:1], 0, v[12:13]
	v_lshl_add_u64 v[20:21], s[0:1], 0, v[20:21]
	v_lshl_add_u64 v[28:29], s[0:1], 0, v[28:29]
	v_lshl_add_u64 v[40:41], s[0:1], 0, v[40:41]
	global_load_dwordx4 v[48:51], v102, s[70:71]
	global_load_dwordx4 v[52:55], v103, s[70:71]
	global_load_dwordx4 v[56:59], v104, s[70:71]
	global_load_dwordx4 v[60:63], v105, s[70:71]
	global_load_dwordx4 v[64:67], v102, s[58:59]
	global_load_dwordx4 v[68:71], v103, s[58:59]
	global_load_dwordx4 v[72:75], v104, s[58:59]
	global_load_dwordx4 v[76:79], v105, s[58:59]
	global_load_dwordx4 v[8:11], v[0:1], off
	global_load_dwordx4 v[4:7], v[0:1], off offset:64
	global_load_dwordx4 v[32:35], v[0:1], off offset:1024
	s_nop 0
	global_load_dwordx4 v[0:3], v[0:1], off offset:1088
	v_lshl_add_u64 v[12:13], v[12:13], 0, s[90:91]
	v_lshl_add_u64 v[20:21], v[20:21], 0, s[90:91]
	v_lshl_add_u64 v[28:29], v[28:29], 0, s[90:91]
	v_lshl_add_u64 v[40:41], v[40:41], 0, s[90:91]
	v_lshl_add_u64 v[16:17], v[12:13], 0, v[90:91]
	v_lshl_add_u64 v[24:25], v[20:21], 0, v[90:91]
	v_lshl_add_u64 v[36:37], v[28:29], 0, v[90:91]
	s_waitcnt vmcnt(28)
; #define LAS __attribute__((address_space(3)))
; #define WAVE_SYNC() asm volatile("s_waitcnt lgkmcnt(0)" ::: "memory")
; __device__ __forceinline__ unsigned f2bf(float f) { unsigned r; asm("v_cvt_pk_bf16_f32 %0, %1, %1" : "=v"(r) : "v"(f)); return r & 0xffffu; }
; __device__ __forceinline__ f32x4 mfma16(bf16x8 a, bf16x8 b, f32x4 c) { return __builtin_amdgcn_mfma_f32_16x16x32_bf16(a, b, c, 0, 0, 0); }
; __device__ __forceinline__ void gl3_item(PREF p, int l, int item, bool valid, LAS unsigned char* sl, int w4, int t256, int lane) {
;     ...
;         for (int nt = 0; nt < 4; ++nt) { const size_t rows = (size_t)(row0 + (nt * 16 + (lane & 15)) * rstride);
; #pragma unroll
;             for (int ks = 0; ks < 2; ++ks) Bk[nt][ks] = *(const bf16x8*)(QK + rows * 1024 + 256 + h * 64 + ks * 32 + (lane >> 4) * 8); }
; #pragma unroll
;         for (int ii = 0; ii < 16; ++ii) { const int i = 16 * w4 + ii; sVt[(2 * lane) * 72 + i] = (bf16_t)(vr[ii] & 0xffffu); sVt[(2 * lane + 1) * 72 + i] = (bf16_t)(vr[ii] >> 16); }
; #pragma unroll
;         for (int d = 0; d < 2; ++d)
; #pragma unroll
;             for (int r = 0; r < 4; ++r) { const int e = (r * 256 + t256) * 8; *(LAS u32x4*)(sS + d * 9216 + (e >> 6) * 72 + (e & 63)) = sv[d][r]; }
;     }
;     __syncthreads();
;     if (valid) {
; #pragma unroll
;         for (int d = 0; d < 2; ++d) {
;             f32x4 att[4];
; #pragma unroll
;             for (int nt = 0; nt < 4; ++nt) { att[nt] = (f32x4){0.f, 0.f, 0.f, 0.f};
; #pragma unroll
;                 for (int ks = 0; ks < 2; ++ks) att[nt] = mfma16(Aq[d][ks], Bk[nt][ks], att[nt]); }
;             if (d == 0) {
; #pragma unroll
;                 for (int nt = 0; nt < 4; ++nt) { const size_t rows = (size_t)(row0 + (nt * 16 + (lane & 15)) * rstride);
; #pragma unroll
;                     for (int ks = 0; ks < 2; ++ks) Bk[nt][ks] = *(const bf16x8*)(QK + rows * 1024 + 512 + 256 + h * 64 + ks * 32 + (lane >> 4) * 8); }
;             }
;             WAVE_SYNC();
; #pragma unroll
;             for (int nt = 0; nt < 4; ++nt)
; #pragma unroll
;                 for (int j = 0; j < 4; ++j) { const int i_ = 16 * w4 + (lane >> 4) * 4 + j, s_ = nt * 16 + (lane & 15); const bool keep = d == 0 ? (s_ <= i_) : (s_ >= i_);
;                     sAtt[i_ * 72 + s_] = keep ? (bf16_t)f2bf(att[nt][j]) : (bf16_t)0; }
	v_lshl_add_u64 v[44:45], v[40:41], 0, v[90:91]
	global_load_dwordx4 v[12:15], v[16:17], off offset:512
	global_load_dwordx4 v[150:153], v[16:17], off offset:1536
	global_load_dwordx4 v[154:157], v[16:17], off offset:1600
	s_nop 0
	global_load_dwordx4 v[16:19], v[16:17], off offset:576
	s_nop 0
	global_load_dwordx4 v[20:23], v[24:25], off offset:512
	global_load_dwordx4 v[158:161], v[24:25], off offset:1536
	global_load_dwordx4 v[162:165], v[24:25], off offset:1600
	s_nop 0
	global_load_dwordx4 v[24:27], v[24:25], off offset:576
	s_nop 0
	global_load_dwordx4 v[28:31], v[36:37], off offset:512
	global_load_dwordx4 v[166:169], v[36:37], off offset:1536
	global_load_dwordx4 v[170:173], v[36:37], off offset:1600
	s_nop 0
	global_load_dwordx4 v[36:39], v[36:37], off offset:576
	s_nop 0
	global_load_dwordx4 v[40:43], v[44:45], off offset:512
	global_load_dwordx4 v[174:177], v[44:45], off offset:1536
	global_load_dwordx4 v[178:181], v[44:45], off offset:1600
	s_nop 0
	global_load_dwordx4 v[44:47], v[44:45], off offset:576
	s_mov_b32 s19, 0x5040100
	s_waitcnt vmcnt(42)
	v_perm_b32 v80, v113, v112, s19
	s_waitcnt vmcnt(40)
	v_perm_b32 v81, v115, v114, s19
	s_waitcnt vmcnt(38)
	v_perm_b32 v82, v117, v116, s19
	s_waitcnt vmcnt(36)
	v_perm_b32 v83, v119, v118, s19
	s_mov_b32 s33, 0x7060302
	ds_write_b128 v89, v[80:83]
	v_perm_b32 v80, v113, v112, s33
	v_perm_b32 v81, v115, v114, s33
	v_perm_b32 v82, v117, v116, s33
	v_perm_b32 v83, v119, v118, s33
	ds_write_b128 v89, v[80:83] offset:144
	s_waitcnt vmcnt(34)
	v_perm_b32 v80, v121, v120, s19
	s_waitcnt vmcnt(32)
	v_perm_b32 v81, v123, v122, s19
	s_waitcnt vmcnt(30)
	v_perm_b32 v82, v125, v124, s19
	s_waitcnt vmcnt(28)
	v_perm_b32 v83, v127, v126, s19
	ds_write_b128 v89, v[80:83] offset:16
	v_perm_b32 v80, v121, v120, s33
	v_perm_b32 v81, v123, v122, s33
	v_perm_b32 v82, v125, v124, s33
	v_perm_b32 v83, v127, v126, s33
	ds_write_b128 v89, v[80:83] offset:160
	s_waitcnt vmcnt(27)
	ds_write_b128 v106, v[48:51] offset:18432
	s_waitcnt vmcnt(26)
	ds_write_b128 v107, v[52:55] offset:18432
	s_waitcnt vmcnt(25)
	ds_write_b128 v108, v[56:59] offset:18432
	s_waitcnt vmcnt(24)
	ds_write_b128 v109, v[60:63] offset:18432
	s_waitcnt vmcnt(23)
	ds_write_b128 v106, v[64:67] offset:36864
	s_waitcnt vmcnt(22)
	ds_write_b128 v107, v[68:71] offset:36864
	s_waitcnt vmcnt(21)
	ds_write_b128 v108, v[72:75] offset:36864
	s_waitcnt vmcnt(20)
	ds_write_b128 v109, v[76:79] offset:36864
.LBB0_92:
	s_andn2_b64 vcc, exec, s[88:89]
	s_waitcnt lgkmcnt(0)
	s_barrier
	s_cbranch_vccnz .LBB0_85
	ds_read_b128 v[48:51], v94
	ds_read_b128 v[52:55], v94 offset:18432
	ds_read_b128 v[56:59], v94 offset:64
	ds_read_b128 v[60:63], v94 offset:18496
	ds_read_b128 v[64:67], v94 offset:2304
	ds_read_b128 v[68:71], v94 offset:20736
	ds_read_b128 v[72:75], v94 offset:2368
	ds_read_b128 v[76:79], v94 offset:20800
	ds_read_b128 v[80:83], v94 offset:4608
	ds_read_b128 v[214:217], v94 offset:23040
	ds_read_b128 v[228:231], v94 offset:4672
	ds_read_b128 v[232:235], v94 offset:23104
	ds_read_b128 v[236:239], v95
	ds_read_b128 v[240:243], v95 offset:18432
	ds_read_b128 v[244:247], v95 offset:64
	ds_read_b128 v[248:251], v95 offset:18496
	v_sub_u32_e32 v136, v84, v92
	s_waitcnt vmcnt(0)
	v_mfma_f32_16x16x32_bf16 v[112:115], v[8:11], v[12:15], 0
	v_mfma_f32_16x16x32_bf16 v[116:119], v[8:11], v[20:23], 0
	v_mfma_f32_16x16x32_bf16 v[120:123], v[8:11], v[28:31], 0
	v_mfma_f32_16x16x32_bf16 v[124:127], v[8:11], v[40:43], 0
	v_mfma_f32_16x16x32_bf16 v[112:115], v[4:7], v[16:19], v[112:115]
	v_mfma_f32_16x16x32_bf16 v[116:119], v[4:7], v[24:27], v[116:119]
	v_mfma_f32_16x16x32_bf16 v[120:123], v[4:7], v[36:39], v[120:123]
	v_mfma_f32_16x16x32_bf16 v[124:127], v[4:7], v[44:47], v[124:127]
	s_nop 7
	s_nop 7
	v_cmp_ge_i32_e64 s[20:21], 0, v136
	v_cmp_ge_i32_e64 s[22:23], 1, v136
	v_cmp_ge_i32_e64 s[24:25], 2, v136
	v_cmp_ge_i32_e64 s[26:27], 3, v136
	v_cndmask_b32_e64 v112, 0, v112, s[20:21]
	v_cndmask_b32_e64 v113, 0, v113, s[22:23]
	v_cndmask_b32_e64 v114, 0, v114, s[24:25]
	v_cndmask_b32_e64 v115, 0, v115, s[26:27]
	v_cvt_pk_bf16_f32 v112, v112, v113
	v_cvt_pk_bf16_f32 v114, v114, v115
	ds_write_b16 v110, v112 offset:55296
	ds_write_b16_d16_hi v110, v112 offset:55440
	ds_write_b16 v110, v114 offset:55584
	ds_write_b16_d16_hi v110, v114 offset:55728
	v_add_u32_e32 v137, 16, v136
	v_cmp_ge_i32_e64 s[20:21], 0, v137
	v_cmp_ge_i32_e64 s[22:23], 1, v137
	v_cmp_ge_i32_e64 s[24:25], 2, v137
	v_cmp_ge_i32_e64 s[26:27], 3, v137
	v_cndmask_b32_e64 v116, 0, v116, s[20:21]
	v_cndmask_b32_e64 v117, 0, v117, s[22:23]
	v_cndmask_b32_e64 v118, 0, v118, s[24:25]
	v_cndmask_b32_e64 v119, 0, v119, s[26:27]
	v_cvt_pk_bf16_f32 v116, v116, v117
	v_cvt_pk_bf16_f32 v118, v118, v119
	ds_write_b16 v110, v116 offset:55328
	ds_write_b16_d16_hi v110, v116 offset:55472
	ds_write_b16 v110, v118 offset:55616
	ds_write_b16_d16_hi v110, v118 offset:55760
	v_add_u32_e32 v137, 32, v136
	v_cmp_ge_i32_e64 s[20:21], 0, v137
	v_cmp_ge_i32_e64 s[22:23], 1, v137
	v_cmp_ge_i32_e64 s[24:25], 2, v137
	v_cmp_ge_i32_e64 s[26:27], 3, v137
	v_cndmask_b32_e64 v120, 0, v120, s[20:21]
	v_cndmask_b32_e64 v121, 0, v121, s[22:23]
	v_cndmask_b32_e64 v122, 0, v122, s[24:25]
	v_cndmask_b32_e64 v123, 0, v123, s[26:27]
	v_cvt_pk_bf16_f32 v120, v120, v121
	v_cvt_pk_bf16_f32 v122, v122, v123
	ds_write_b16 v110, v120 offset:55360
	ds_write_b16_d16_hi v110, v120 offset:55504
	ds_write_b16 v110, v122 offset:55648
	ds_write_b16_d16_hi v110, v122 offset:55792
	v_add_u32_e32 v137, 48, v136
	v_cmp_ge_i32_e64 s[20:21], 0, v137
	v_cmp_ge_i32_e64 s[22:23], 1, v137
	v_cmp_ge_i32_e64 s[24:25], 2, v137
	v_cmp_ge_i32_e64 s[26:27], 3, v137
	v_cndmask_b32_e64 v124, 0, v124, s[20:21]
	v_cndmask_b32_e64 v125, 0, v125, s[22:23]
	v_cndmask_b32_e64 v126, 0, v126, s[24:25]
	v_cndmask_b32_e64 v127, 0, v127, s[26:27]
	v_cvt_pk_bf16_f32 v124, v124, v125
	v_cvt_pk_bf16_f32 v126, v126, v127
	ds_write_b16 v111, v124 offset:55296
	ds_write_b16_d16_hi v111, v124 offset:55440
	ds_write_b16 v111, v126 offset:55584
	ds_write_b16_d16_hi v111, v126 offset:55728
	s_waitcnt lgkmcnt(0)
; #define LAS __attribute__((address_space(3)))
; #define WAVE_SYNC() asm volatile("s_waitcnt lgkmcnt(0)" ::: "memory")
; __device__ __forceinline__ unsigned f2bf(float f) { unsigned r; asm("v_cvt_pk_bf16_f32 %0, %1, %1" : "=v"(r) : "v"(f)); return r & 0xffffu; }
; __device__ __forceinline__ f32x4 mfma16(bf16x8 a, bf16x8 b, f32x4 c) { return __builtin_amdgcn_mfma_f32_16x16x32_bf16(a, b, c, 0, 0, 0); }
; __device__ __forceinline__ void gl3_item(PREF p, int l, int item, bool valid, LAS unsigned char* sl, int w4, int t256, int lane) {
;     ...
;         for (int d = 0; d < 2; ++d) {
;             f32x4 att[4];
; #pragma unroll
;             for (int nt = 0; nt < 4; ++nt) { att[nt] = (f32x4){0.f, 0.f, 0.f, 0.f};
; #pragma unroll
;                 for (int ks = 0; ks < 2; ++ks) att[nt] = mfma16(Aq[d][ks], Bk[nt][ks], att[nt]); }
;             if (d == 0) {
; #pragma unroll
;                 for (int nt = 0; nt < 4; ++nt) { const size_t rows = (size_t)(row0 + (nt * 16 + (lane & 15)) * rstride);
; #pragma unroll
;                     for (int ks = 0; ks < 2; ++ks) Bk[nt][ks] = *(const bf16x8*)(QK + rows * 1024 + 512 + 256 + h * 64 + ks * 32 + (lane >> 4) * 8); }
;             }
;             WAVE_SYNC();
; #pragma unroll
;             for (int nt = 0; nt < 4; ++nt)
; #pragma unroll
;                 for (int j = 0; j < 4; ++j) { const int i_ = 16 * w4 + (lane >> 4) * 4 + j, s_ = nt * 16 + (lane & 15); const bool keep = d == 0 ? (s_ <= i_) : (s_ >= i_);
;                     sAtt[i_ * 72 + s_] = keep ? (bf16_t)f2bf(att[nt][j]) : (bf16_t)0; }
;             WAVE_SYNC();
;             bf16x8 Aa[2];
; #pragma unroll
;             for (int ks = 0; ks < 2; ++ks) Aa[ks] = *(const LAS bf16x8*)(sAtt + (16 * w4 + (lane & 15)) * 72 + ks * 32 + (lane >> 4) * 8);
; #pragma unroll
;             for (int nt = 0; nt < 8; ++nt)
; #pragma unroll
;                 for (int ks = 0; ks < 2; ++ks) { const int bo = (nt * 16 + (lane & 15)) * 72 + ks * 32 + (lane >> 4) * 8;
;                     o[nt] = mfma16(Aa[ks], *(const LAS bf16x8*)(sVt + bo), o[nt]); o[nt] = mfma16(Aq[d][ks], *(const LAS bf16x8*)(sS + d * 9216 + bo), o[nt]); }
	ds_read_b128 v[128:131], v93 offset:55296
	ds_read_b128 v[132:135], v93 offset:55360
	s_waitcnt lgkmcnt(0)
	v_mfma_f32_16x16x32_bf16 v[182:185], v[128:131], v[48:51], 0
	v_mfma_f32_16x16x32_bf16 v[186:189], v[128:131], v[64:67], 0
	v_mfma_f32_16x16x32_bf16 v[182:185], v[8:11], v[52:55], v[182:185]
	v_mfma_f32_16x16x32_bf16 v[186:189], v[8:11], v[68:71], v[186:189]
	v_mfma_f32_16x16x32_bf16 v[182:185], v[132:135], v[56:59], v[182:185]
	v_mfma_f32_16x16x32_bf16 v[186:189], v[132:135], v[72:75], v[186:189]
	v_mfma_f32_16x16x32_bf16 v[182:185], v[4:7], v[60:63], v[182:185]
	v_mfma_f32_16x16x32_bf16 v[186:189], v[4:7], v[76:79], v[186:189]
	ds_read_b128 v[48:51], v94 offset:9216
	ds_read_b128 v[52:55], v94 offset:27648
	ds_read_b128 v[56:59], v94 offset:9280
	ds_read_b128 v[60:63], v94 offset:27712
	ds_read_b128 v[64:67], v94 offset:11520
	ds_read_b128 v[68:71], v94 offset:29952
	ds_read_b128 v[72:75], v94 offset:11584
	ds_read_b128 v[76:79], v94 offset:30016
	v_mfma_f32_16x16x32_bf16 v[190:193], v[128:131], v[80:83], 0
	v_mfma_f32_16x16x32_bf16 v[194:197], v[128:131], v[236:239], 0
	v_mfma_f32_16x16x32_bf16 v[190:193], v[8:11], v[214:217], v[190:193]
	v_mfma_f32_16x16x32_bf16 v[194:197], v[8:11], v[240:243], v[194:197]
	v_mfma_f32_16x16x32_bf16 v[190:193], v[132:135], v[228:231], v[190:193]
	v_mfma_f32_16x16x32_bf16 v[194:197], v[132:135], v[244:247], v[194:197]
	v_mfma_f32_16x16x32_bf16 v[190:193], v[4:7], v[232:235], v[190:193]
	v_mfma_f32_16x16x32_bf16 v[194:197], v[4:7], v[248:251], v[194:197]
	ds_read_b128 v[80:83], v94 offset:13824
	ds_read_b128 v[214:217], v94 offset:32256
	ds_read_b128 v[228:231], v94 offset:13888
	ds_read_b128 v[232:235], v94 offset:32320
	ds_read_b128 v[236:239], v96
	ds_read_b128 v[240:243], v96 offset:18432
	ds_read_b128 v[244:247], v96 offset:64
	ds_read_b128 v[248:251], v96 offset:18496
	s_waitcnt lgkmcnt(8)
	v_mfma_f32_16x16x32_bf16 v[198:201], v[128:131], v[48:51], 0
	v_mfma_f32_16x16x32_bf16 v[202:205], v[128:131], v[64:67], 0
	v_mfma_f32_16x16x32_bf16 v[198:201], v[8:11], v[52:55], v[198:201]
	v_mfma_f32_16x16x32_bf16 v[202:205], v[8:11], v[68:71], v[202:205]
	v_mfma_f32_16x16x32_bf16 v[198:201], v[132:135], v[56:59], v[198:201]
	v_mfma_f32_16x16x32_bf16 v[202:205], v[132:135], v[72:75], v[202:205]
	v_mfma_f32_16x16x32_bf16 v[198:201], v[4:7], v[60:63], v[198:201]
	v_mfma_f32_16x16x32_bf16 v[202:205], v[4:7], v[76:79], v[202:205]
	ds_read_b128 v[48:51], v94
	ds_read_b128 v[52:55], v94 offset:36864
	ds_read_b128 v[56:59], v94 offset:64
	ds_read_b128 v[60:63], v94 offset:36928
	ds_read_b128 v[64:67], v94 offset:2304
	ds_read_b128 v[68:71], v94 offset:39168
	ds_read_b128 v[72:75], v94 offset:2368
	ds_read_b128 v[76:79], v94 offset:39232
	s_waitcnt lgkmcnt(8)
	v_mfma_f32_16x16x32_bf16 v[206:209], v[128:131], v[80:83], 0
	v_mfma_f32_16x16x32_bf16 v[210:213], v[128:131], v[236:239], 0
	v_mfma_f32_16x16x32_bf16 v[206:209], v[8:11], v[214:217], v[206:209]
	v_mfma_f32_16x16x32_bf16 v[210:213], v[8:11], v[240:243], v[210:213]
	v_mfma_f32_16x16x32_bf16 v[206:209], v[132:135], v[228:231], v[206:209]
	v_mfma_f32_16x16x32_bf16 v[210:213], v[132:135], v[244:247], v[210:213]
	v_mfma_f32_16x16x32_bf16 v[206:209], v[4:7], v[232:235], v[206:209]
	v_mfma_f32_16x16x32_bf16 v[210:213], v[4:7], v[248:251], v[210:213]
	ds_read_b128 v[80:83], v94 offset:4608
	ds_read_b128 v[214:217], v94 offset:41472
	ds_read_b128 v[228:231], v94 offset:4672
	ds_read_b128 v[232:235], v94 offset:41536
	ds_read_b128 v[236:239], v95
	ds_read_b128 v[240:243], v95 offset:36864
	ds_read_b128 v[244:247], v95 offset:64
	ds_read_b128 v[248:251], v95 offset:36928
	v_mfma_f32_16x16x32_bf16 v[112:115], v[32:35], v[150:153], 0
	v_mfma_f32_16x16x32_bf16 v[116:119], v[32:35], v[158:161], 0
	v_mfma_f32_16x16x32_bf16 v[120:123], v[32:35], v[166:169], 0
	v_mfma_f32_16x16x32_bf16 v[124:127], v[32:35], v[174:177], 0
	v_mfma_f32_16x16x32_bf16 v[112:115], v[0:3], v[154:157], v[112:115]
	v_mfma_f32_16x16x32_bf16 v[116:119], v[0:3], v[162:165], v[116:119]
	v_mfma_f32_16x16x32_bf16 v[120:123], v[0:3], v[170:173], v[120:123]
	v_mfma_f32_16x16x32_bf16 v[124:127], v[0:3], v[178:181], v[124:127]
	s_nop 7
	s_nop 7
	v_cmp_le_i32_e64 s[20:21], 0, v136
	v_cmp_le_i32_e64 s[22:23], 1, v136
	v_cmp_le_i32_e64 s[24:25], 2, v136
	v_cmp_le_i32_e64 s[26:27], 3, v136
	v_cndmask_b32_e64 v112, 0, v112, s[20:21]
	v_cndmask_b32_e64 v113, 0, v113, s[22:23]
	v_cndmask_b32_e64 v114, 0, v114, s[24:25]
	v_cndmask_b32_e64 v115, 0, v115, s[26:27]
	v_cvt_pk_bf16_f32 v112, v112, v113
	v_cvt_pk_bf16_f32 v114, v114, v115
	ds_write_b16 v110, v112 offset:55296
	ds_write_b16_d16_hi v110, v112 offset:55440
	ds_write_b16 v110, v114 offset:55584
	ds_write_b16_d16_hi v110, v114 offset:55728
	v_add_u32_e32 v137, 16, v136
	v_cmp_le_i32_e64 s[20:21], 0, v137
	v_cmp_le_i32_e64 s[22:23], 1, v137
	v_cmp_le_i32_e64 s[24:25], 2, v137
	v_cmp_le_i32_e64 s[26:27], 3, v137
	v_cndmask_b32_e64 v116, 0, v116, s[20:21]
	v_cndmask_b32_e64 v117, 0, v117, s[22:23]
	v_cndmask_b32_e64 v118, 0, v118, s[24:25]
	v_cndmask_b32_e64 v119, 0, v119, s[26:27]
	v_cvt_pk_bf16_f32 v116, v116, v117
	v_cvt_pk_bf16_f32 v118, v118, v119
	ds_write_b16 v110, v116 offset:55328
	ds_write_b16_d16_hi v110, v116 offset:55472
	ds_write_b16 v110, v118 offset:55616
	ds_write_b16_d16_hi v110, v118 offset:55760
	v_add_u32_e32 v137, 32, v136
	v_cmp_le_i32_e64 s[20:21], 0, v137
	v_cmp_le_i32_e64 s[22:23], 1, v137
	v_cmp_le_i32_e64 s[24:25], 2, v137
	v_cmp_le_i32_e64 s[26:27], 3, v137
	v_cndmask_b32_e64 v120, 0, v120, s[20:21]
	v_cndmask_b32_e64 v121, 0, v121, s[22:23]
	v_cndmask_b32_e64 v122, 0, v122, s[24:25]
	v_cndmask_b32_e64 v123, 0, v123, s[26:27]
	v_cvt_pk_bf16_f32 v120, v120, v121
	v_cvt_pk_bf16_f32 v122, v122, v123
	ds_write_b16 v110, v120 offset:55360
	ds_write_b16_d16_hi v110, v120 offset:55504
	ds_write_b16 v110, v122 offset:55648
	ds_write_b16_d16_hi v110, v122 offset:55792
	v_add_u32_e32 v137, 48, v136
	v_cmp_le_i32_e64 s[20:21], 0, v137
	v_cmp_le_i32_e64 s[22:23], 1, v137
	v_cmp_le_i32_e64 s[24:25], 2, v137
	v_cmp_le_i32_e64 s[26:27], 3, v137
	v_cndmask_b32_e64 v124, 0, v124, s[20:21]
	v_cndmask_b32_e64 v125, 0, v125, s[22:23]
	v_cndmask_b32_e64 v126, 0, v126, s[24:25]
	v_cndmask_b32_e64 v127, 0, v127, s[26:27]
	v_cvt_pk_bf16_f32 v124, v124, v125
	v_cvt_pk_bf16_f32 v126, v126, v127
	ds_write_b16 v111, v124 offset:55296
	ds_write_b16_d16_hi v111, v124 offset:55440
	ds_write_b16 v111, v126 offset:55584
	ds_write_b16_d16_hi v111, v126 offset:55728
	s_waitcnt lgkmcnt(0)
; #define LAS __attribute__((address_space(3)))
; #define WAVE_SYNC() asm volatile("s_waitcnt lgkmcnt(0)" ::: "memory")
; __device__ __forceinline__ unsigned f2bf(float f) { unsigned r; asm("v_cvt_pk_bf16_f32 %0, %1, %1" : "=v"(r) : "v"(f)); return r & 0xffffu; }
; __device__ __forceinline__ f32x4 mfma16(bf16x8 a, bf16x8 b, f32x4 c) { return __builtin_amdgcn_mfma_f32_16x16x32_bf16(a, b, c, 0, 0, 0); }
; __device__ __forceinline__ void gl3_item(PREF p, int l, int item, bool valid, LAS unsigned char* sl, int w4, int t256, int lane) {
;     ...
; #pragma unroll
;             for (int nt = 0; nt < 4; ++nt)
; #pragma unroll
;                 for (int j = 0; j < 4; ++j) { const int i_ = 16 * w4 + (lane >> 4) * 4 + j, s_ = nt * 16 + (lane & 15); const bool keep = d == 0 ? (s_ <= i_) : (s_ >= i_);
;                     sAtt[i_ * 72 + s_] = keep ? (bf16_t)f2bf(att[nt][j]) : (bf16_t)0; }
;             WAVE_SYNC();
;             bf16x8 Aa[2];
; #pragma unroll
;             for (int ks = 0; ks < 2; ++ks) Aa[ks] = *(const LAS bf16x8*)(sAtt + (16 * w4 + (lane & 15)) * 72 + ks * 32 + (lane >> 4) * 8);
; #pragma unroll
;             for (int nt = 0; nt < 8; ++nt)
; #pragma unroll
;                 for (int ks = 0; ks < 2; ++ks) { const int bo = (nt * 16 + (lane & 15)) * 72 + ks * 32 + (lane >> 4) * 8;
;                     o[nt] = mfma16(Aa[ks], *(const LAS bf16x8*)(sVt + bo), o[nt]); o[nt] = mfma16(Aq[d][ks], *(const LAS bf16x8*)(sS + d * 9216 + bo), o[nt]); }
;         }
;         const float* gn = p.gla_norm_g + l * 512 + h * 128;
	ds_read_b128 v[128:131], v93 offset:55296
	ds_read_b128 v[132:135], v93 offset:55360
	s_waitcnt lgkmcnt(0)
	v_mfma_f32_16x16x32_bf16 v[182:185], v[128:131], v[48:51], v[182:185]
	v_mfma_f32_16x16x32_bf16 v[186:189], v[128:131], v[64:67], v[186:189]
	v_mfma_f32_16x16x32_bf16 v[182:185], v[32:35], v[52:55], v[182:185]
	v_mfma_f32_16x16x32_bf16 v[186:189], v[32:35], v[68:71], v[186:189]
	v_mfma_f32_16x16x32_bf16 v[182:185], v[132:135], v[56:59], v[182:185]
	v_mfma_f32_16x16x32_bf16 v[186:189], v[132:135], v[72:75], v[186:189]
	v_mfma_f32_16x16x32_bf16 v[182:185], v[0:3], v[60:63], v[182:185]
	v_mfma_f32_16x16x32_bf16 v[186:189], v[0:3], v[76:79], v[186:189]
	ds_read_b128 v[48:51], v94 offset:9216
	ds_read_b128 v[52:55], v94 offset:46080
	ds_read_b128 v[56:59], v94 offset:9280
	ds_read_b128 v[60:63], v94 offset:46144
	ds_read_b128 v[64:67], v94 offset:11520
	ds_read_b128 v[68:71], v94 offset:48384
	ds_read_b128 v[72:75], v94 offset:11584
	ds_read_b128 v[76:79], v94 offset:48448
	v_mfma_f32_16x16x32_bf16 v[190:193], v[128:131], v[80:83], v[190:193]
	v_mfma_f32_16x16x32_bf16 v[194:197], v[128:131], v[236:239], v[194:197]
	v_mfma_f32_16x16x32_bf16 v[190:193], v[32:35], v[214:217], v[190:193]
	v_mfma_f32_16x16x32_bf16 v[194:197], v[32:35], v[240:243], v[194:197]
	v_mfma_f32_16x16x32_bf16 v[190:193], v[132:135], v[228:231], v[190:193]
	v_mfma_f32_16x16x32_bf16 v[194:197], v[132:135], v[244:247], v[194:197]
	v_mfma_f32_16x16x32_bf16 v[190:193], v[0:3], v[232:235], v[190:193]
	v_mfma_f32_16x16x32_bf16 v[194:197], v[0:3], v[248:251], v[194:197]
	ds_read_b128 v[80:83], v94 offset:13824
	ds_read_b128 v[214:217], v94 offset:50688
	ds_read_b128 v[228:231], v94 offset:13888
	ds_read_b128 v[232:235], v94 offset:50752
	ds_read_b128 v[236:239], v96
	ds_read_b128 v[240:243], v96 offset:36864
	ds_read_b128 v[244:247], v96 offset:64
	ds_read_b128 v[248:251], v96 offset:36928
	s_waitcnt lgkmcnt(8)
	v_mfma_f32_16x16x32_bf16 v[198:201], v[128:131], v[48:51], v[198:201]
	v_mfma_f32_16x16x32_bf16 v[202:205], v[128:131], v[64:67], v[202:205]
	v_mfma_f32_16x16x32_bf16 v[198:201], v[32:35], v[52:55], v[198:201]
	v_mfma_f32_16x16x32_bf16 v[202:205], v[32:35], v[68:71], v[202:205]
	v_mfma_f32_16x16x32_bf16 v[198:201], v[132:135], v[56:59], v[198:201]
	v_mfma_f32_16x16x32_bf16 v[202:205], v[132:135], v[72:75], v[202:205]
	v_mfma_f32_16x16x32_bf16 v[198:201], v[0:3], v[60:63], v[198:201]
	v_mfma_f32_16x16x32_bf16 v[202:205], v[0:3], v[76:79], v[202:205]
	s_waitcnt lgkmcnt(0)
	v_mfma_f32_16x16x32_bf16 v[206:209], v[128:131], v[80:83], v[206:209]
	v_mfma_f32_16x16x32_bf16 v[210:213], v[128:131], v[236:239], v[210:213]
	v_mfma_f32_16x16x32_bf16 v[206:209], v[32:35], v[214:217], v[206:209]
	v_mfma_f32_16x16x32_bf16 v[210:213], v[32:35], v[240:243], v[210:213]
	v_mfma_f32_16x16x32_bf16 v[206:209], v[132:135], v[228:231], v[206:209]
	v_mfma_f32_16x16x32_bf16 v[210:213], v[132:135], v[244:247], v[210:213]
	v_mfma_f32_16x16x32_bf16 v[206:209], v[0:3], v[232:235], v[206:209]
	v_mfma_f32_16x16x32_bf16 v[210:213], v[0:3], v[248:251], v[210:213]
	s_movk_i32 s46, 0x1600
	s_lshl_b32 s90, s16, 8
	s_movk_i32 s33, 0x1000
	s_lshl_b32 s16, s16, 9
	s_add_u32 s88, s10, s16
	s_addc_u32 s89, s11, 0
	s_mov_b64 s[70:71], 0x1000
	s_nop 7
	s_nop 7
	v_mov_b32_e32 v24, v182
	v_mov_b32_e32 v25, v183
	v_mov_b32_e32 v26, v184
	v_mov_b32_e32 v27, v185
	v_mov_b32_e32 v28, v186
	v_mov_b32_e32 v29, v187
	v_mov_b32_e32 v30, v188
	v_mov_b32_e32 v31, v189
	v_mov_b32_e32 v20, v190
	v_mov_b32_e32 v21, v191
	v_mov_b32_e32 v22, v192
	v_mov_b32_e32 v23, v193
	v_mov_b32_e32 v16, v194
	v_mov_b32_e32 v17, v195
	v_mov_b32_e32 v18, v196
	v_mov_b32_e32 v19, v197
	v_mov_b32_e32 v12, v198
	v_mov_b32_e32 v13, v199
	v_mov_b32_e32 v14, v200
	v_mov_b32_e32 v15, v201
	v_mov_b32_e32 v8, v202
	v_mov_b32_e32 v9, v203
	v_mov_b32_e32 v10, v204
	v_mov_b32_e32 v11, v205
	v_mov_b32_e32 v4, v206
	v_mov_b32_e32 v5, v207
	v_mov_b32_e32 v6, v208
	v_mov_b32_e32 v7, v209
	v_mov_b32_e32 v0, v210
	v_mov_b32_e32 v1, v211
	v_mov_b32_e32 v2, v212
	v_mov_b32_e32 v3, v213
	s_branch .Lgl3b_epi
